# P6 PLE-gate epilogue: rolling window of XB/PP loads, fire-and-forget stores, next-unit rstd prefetch (on top of P4 change)
# speedup vs baseline: 1.0221x; 1.0109x over previous
.LBB0_1008:
	s_add_u32 s6, s84, 0x2300000
	s_addc_u32 s7, s85, 0
	s_add_u32 s8, s84, 0x2d300000
	v_readlane_b32 s10, v255, 6
	s_addc_u32 s9, s85, 0
	v_readlane_b32 s11, v255, 7
	s_lshl_b32 s10, s10, 5
	s_and_b32 s16, s10, 0x60
	s_mov_b64 s[10:11], 0x80
	s_add_i32 m0, s27, 0x18000
	v_lshl_add_u64 v[6:7], v[6:7], 0, s[10:11]
	s_lshl_b32 s1, s0, 13
	s_lshr_b32 s15, s16, 3
	s_waitcnt vmcnt(2)
	s_barrier
	global_load_lds_dwordx4 v[6:7], off
	v_lshl_add_u64 v[4:5], v[4:5], 0, s[10:11]
	s_add_i32 m0, s27, 0x1a000
	s_add_i32 s42, s27, 0x8000
	s_add_i32 s43, s27, 0xa000
	global_load_lds_dwordx4 v[4:5], off
	v_lshl_add_u64 v[0:1], v[0:1], 0, s[10:11]
	s_mov_b32 m0, s42
	s_add_u32 s12, s28, 0x40080
	global_load_lds_dwordx4 v[0:1], off
	v_lshl_add_u64 v[0:1], v[2:3], 0, s[10:11]
	s_mov_b32 m0, s43
	s_addc_u32 s13, s29, 0
	global_load_lds_dwordx4 v[0:1], off
	s_add_i32 m0, s27, 0x1c000
	v_lshl_add_u64 v[0:1], s[12:13], 0, v[132:133]
	global_load_lds_dwordx4 v[0:1], off
	v_lshl_add_u64 v[0:1], s[12:13], 0, v[128:129]
	s_add_i32 m0, s27, 0x1e000
	v_and_b32_e32 v3, 48, v9
	global_load_lds_dwordx4 v[0:1], off
	v_and_b32_e32 v0, 15, v9
	v_lshl_or_b32 v152, s0, 6, v0
	v_ashrrev_i32_e32 v2, 6, v9
	v_lshl_or_b32 v0, v0, 6, v3
	v_lshlrev_b32_e32 v3, 2, v9
	v_lshl_add_u32 v4, v2, 10, s1
	v_and_b32_e32 v3, 32, v3
	v_add_lshl_u32 v2, v2, s15, 10
	v_ashrrev_i32_e32 v1, 1, v9
	v_bitop3_b32 v4, v0, v4, v3 bitop3:0xde
	v_bitop3_b32 v153, v0, v2, v3 bitop3:0xde
	v_lshlrev_b32_e32 v0, 14, v12
	v_and_b32_e32 v1, -8, v1
	v_and_b32_e32 v0, 0xffff8000, v0
	v_readlane_b32 s12, v255, 0
	v_add_u32_e32 v154, s16, v1
	v_lshl_add_u32 v0, v13, 11, v0
	v_and_b32_e32 v1, 1, v12
	v_readlane_b32 s13, v255, 1
	v_lshl_or_b32 v0, v1, 6, v0
	s_load_dwordx2 s[12:13], s[12:13], 0xc8
	v_lshl_add_u32 v136, v14, 1, v0
	v_lshlrev_b32_e32 v0, 14, v8
	v_and_b32_e32 v0, 0xffff8000, v0
	s_waitcnt vmcnt(6)
	s_cmpk_lt_u32 s82, 0x100
	v_lshl_add_u32 v0, v10, 11, v0
	v_and_b32_e32 v1, 1, v8
	s_sext_i32_i8 s48, s14
	s_cselect_b64 s[14:15], -1, 0
	v_lshl_or_b32 v0, v1, 6, v0
	s_add_i32 s45, 0, 0x10000
	s_add_i32 s46, 0, 0x14000
	s_ashr_i32 s44, s67, 31
	v_mov_b32_e32 v137, v133
	v_lshl_add_u32 v138, v11, 1, v0
	v_mov_b32_e32 v139, v133
	v_mov_b64_e32 v[140:141], 0x410
	v_mov_b64_e32 v[142:143], 0x40f
	v_add_u32_e32 v155, s45, v153
	v_add_u32_e32 v156, s46, v153
	v_add_u32_e32 v157, 0, v4
	v_mov_b32_e32 v158, 0x358637bd
	s_mov_b32 s47, 0x800000
	s_barrier
	v_lshl_add_u32 v144, s26, 8, v152
	v_mov_b32_e32 v145, 0
	v_lshlrev_b64 v[144:145], 6, v[144:145]
	v_and_b32_e32 v146, 24, v154
	v_lshlrev_b32_e32 v146, 1, v146
	v_mov_b32_e32 v147, 0
	v_lshl_add_u64 v[144:145], s[6:7], 0, v[144:145]
	v_lshl_add_u64 v[144:145], v[144:145], 0, v[146:147]
	global_load_dwordx4 v[112:115], v[144:145], off
	global_load_dwordx4 v[116:119], v[144:145], off offset:1024
	global_load_dwordx4 v[120:123], v[144:145], off offset:2048
	global_load_dwordx4 v[124:127], v[144:145], off offset:3072
	v_add_co_u32_e32 v144, vcc, 0x2000, v144
	s_nop 1
	v_addc_co_u32_e32 v145, vcc, 0, v145, vcc
	global_load_dwordx4 v[96:99], v[144:145], off
	global_load_dwordx4 v[100:103], v[144:145], off offset:1024
	global_load_dwordx4 v[104:107], v[144:145], off offset:2048
	global_load_dwordx4 v[108:111], v[144:145], off offset:3072
	s_waitcnt vmcnt(0)
	v_add_f32_e32 v112, v112, v113
	v_add_f32_e32 v116, v116, v117
	v_add_f32_e32 v120, v120, v121
	v_add_f32_e32 v124, v124, v125
	v_add_f32_e32 v96, v96, v97
	v_add_f32_e32 v100, v100, v101
	v_add_f32_e32 v104, v104, v105
	v_add_f32_e32 v108, v108, v109
	v_add_f32_e32 v114, v114, v115
	v_add_f32_e32 v118, v118, v119
	v_add_f32_e32 v122, v122, v123
	v_add_f32_e32 v126, v126, v127
	v_add_f32_e32 v98, v98, v99
	v_add_f32_e32 v102, v102, v103
	v_add_f32_e32 v106, v106, v107
	v_add_f32_e32 v110, v110, v111
	v_add_f32_e32 v112, v112, v114
	v_add_f32_e32 v116, v116, v118
	v_add_f32_e32 v120, v120, v122
	v_add_f32_e32 v124, v124, v126
	v_add_f32_e32 v96, v96, v98
	v_add_f32_e32 v100, v100, v102
	v_add_f32_e32 v104, v104, v106
	v_add_f32_e32 v108, v108, v110
	v_mov_b32_e32 v113, v112
	v_mov_b32_e32 v117, v116
	v_mov_b32_e32 v121, v120
	v_mov_b32_e32 v125, v124
	v_mov_b32_e32 v97, v96
	v_mov_b32_e32 v101, v100
	v_mov_b32_e32 v105, v104
	v_mov_b32_e32 v109, v108
	v_permlane16_swap_b32_e32 v113, v112
	v_permlane16_swap_b32_e32 v117, v116
	v_permlane16_swap_b32_e32 v121, v120
	v_permlane16_swap_b32_e32 v125, v124
	v_permlane16_swap_b32_e32 v97, v96
	v_permlane16_swap_b32_e32 v101, v100
	v_permlane16_swap_b32_e32 v105, v104
	v_permlane16_swap_b32_e32 v109, v108
	v_add_f32_e32 v112, v112, v113
	v_add_f32_e32 v116, v116, v117
	v_add_f32_e32 v120, v120, v121
	v_add_f32_e32 v124, v124, v125
	v_add_f32_e32 v96, v96, v97
	v_add_f32_e32 v100, v100, v101
	v_add_f32_e32 v104, v104, v105
	v_add_f32_e32 v108, v108, v109
	v_mov_b32_e32 v113, v112
	v_mov_b32_e32 v117, v116
	v_mov_b32_e32 v121, v120
	v_mov_b32_e32 v125, v124
	v_mov_b32_e32 v97, v96
	v_mov_b32_e32 v101, v100
	v_mov_b32_e32 v105, v104
	v_mov_b32_e32 v109, v108
	v_permlane32_swap_b32_e32 v113, v112
	v_permlane32_swap_b32_e32 v117, v116
	v_permlane32_swap_b32_e32 v121, v120
	v_permlane32_swap_b32_e32 v125, v124
	v_permlane32_swap_b32_e32 v97, v96
	v_permlane32_swap_b32_e32 v101, v100
	v_permlane32_swap_b32_e32 v105, v104
	v_permlane32_swap_b32_e32 v109, v108
	v_add_f32_e32 v112, v112, v113
	v_add_f32_e32 v116, v116, v117
	v_add_f32_e32 v120, v120, v121
	v_add_f32_e32 v124, v124, v125
	v_add_f32_e32 v96, v96, v97
	v_add_f32_e32 v100, v100, v101
	v_add_f32_e32 v104, v104, v105
	v_add_f32_e32 v108, v108, v109
	v_fmamk_f32 v112, v112, 0x3a800000, v158
	v_fmamk_f32 v116, v116, 0x3a800000, v158
	v_fmamk_f32 v120, v120, 0x3a800000, v158
	v_fmamk_f32 v124, v124, 0x3a800000, v158
	v_fmamk_f32 v96, v96, 0x3a800000, v158
	v_fmamk_f32 v100, v100, 0x3a800000, v158
	v_fmamk_f32 v104, v104, 0x3a800000, v158
	v_fmamk_f32 v108, v108, 0x3a800000, v158
	v_rsq_f32_e32 v226, v112
	v_rsq_f32_e32 v228, v116
	v_rsq_f32_e32 v230, v120
	v_rsq_f32_e32 v232, v124
	v_rsq_f32_e32 v234, v96
	v_rsq_f32_e32 v236, v100
	v_rsq_f32_e32 v238, v104
	v_rsq_f32_e32 v240, v108
	s_branch .LBB0_1011

.LBB0_1017:
	v_lshl_add_u32 v148, s26, 8, v152
	v_mov_b32_e32 v149, 0
	v_lshl_add_u32 v146, s48, 8, v154
	v_mov_b32_e32 v147, 0
	v_lshlrev_b64 v[150:151], 11, v[148:149]
	v_lshlrev_b64 v[144:145], 1, v[146:147]
	v_lshl_add_u64 v[250:251], s[2:3], 0, v[150:151]
	v_lshl_add_u64 v[250:251], v[250:251], 0, v[144:145]
	v_lshl_add_u64 v[252:253], s[8:9], 0, v[150:151]
	v_lshl_add_u64 v[252:253], v[252:253], 0, v[144:145]
	v_lshlrev_b64 v[150:151], 12, v[148:149]
	v_lshlrev_b64 v[144:145], 2, v[146:147]
	v_lshl_add_u64 v[224:225], s[12:13], 0, v[150:151]
	v_lshl_add_u64 v[224:225], v[224:225], 0, v[144:145]
	s_mov_b64 s[28:29], 0x8000
	s_mov_b64 s[30:31], 0x28000
	s_mov_b64 s[50:51], 0x10000
	s_mov_b64 s[52:53], 0x50000
	s_and_b64 vcc, s[0:1], exec
	s_cselect_b32 s17, s18, s26
	global_load_dwordx4 v[160:163], v[250:251], off
	global_load_dwordx4 v[164:167], v[252:253], off nt
	global_load_dwordx4 v[168:171], v[250:251], off offset:256
	global_load_dwordx4 v[172:175], v[252:253], off offset:256 nt
	v_lshl_add_u64 v[250:251], v[250:251], 0, s[28:29]
	v_lshl_add_u64 v[252:253], v[252:253], 0, s[28:29]
	global_load_dwordx4 v[176:179], v[250:251], off
	global_load_dwordx4 v[180:183], v[252:253], off nt
	global_load_dwordx4 v[184:187], v[250:251], off offset:256
	global_load_dwordx4 v[188:191], v[252:253], off offset:256 nt
	v_lshl_add_u64 v[250:251], v[250:251], 0, s[28:29]
	v_lshl_add_u64 v[252:253], v[252:253], 0, s[28:29]
	global_load_dwordx4 v[192:195], v[250:251], off
	global_load_dwordx4 v[196:199], v[252:253], off nt
	global_load_dwordx4 v[200:203], v[250:251], off offset:256
	global_load_dwordx4 v[204:207], v[252:253], off offset:256 nt
	v_lshl_add_u64 v[250:251], v[250:251], 0, s[28:29]
	v_lshl_add_u64 v[252:253], v[252:253], 0, s[28:29]
	global_load_dwordx4 v[208:211], v[250:251], off
	global_load_dwordx4 v[212:215], v[252:253], off nt
	global_load_dwordx4 v[216:219], v[250:251], off offset:256
	global_load_dwordx4 v[220:223], v[252:253], off offset:256 nt
	v_lshl_add_u64 v[250:251], v[250:251], 0, s[30:31]
	v_lshl_add_u64 v[252:253], v[252:253], 0, s[30:31]
	s_waitcnt vmcnt(12)
	v_pk_mul_f32 v[124:125], v[124:125], v[226:227] op_sel_hi:[1,0]
	v_pk_mul_f32 v[126:127], v[126:127], v[226:227] op_sel_hi:[1,0]
	v_pk_mul_f32 v[120:121], v[120:121], v[226:227] op_sel_hi:[1,0]
	v_pk_mul_f32 v[122:123], v[122:123], v[226:227] op_sel_hi:[1,0]
	v_mul_f32_e32 v124, 0xbfb8aa3b, v124
	v_mul_f32_e32 v125, 0xbfb8aa3b, v125
	v_mul_f32_e32 v126, 0xbfb8aa3b, v126
	v_mul_f32_e32 v127, 0xbfb8aa3b, v127
	v_mul_f32_e32 v120, 0xbfb8aa3b, v120
	v_mul_f32_e32 v121, 0xbfb8aa3b, v121
	v_mul_f32_e32 v122, 0xbfb8aa3b, v122
	v_mul_f32_e32 v123, 0xbfb8aa3b, v123
	v_exp_f32_e32 v124, v124
	v_exp_f32_e32 v125, v125
	v_exp_f32_e32 v126, v126
	v_exp_f32_e32 v127, v127
	v_exp_f32_e32 v120, v120
	v_exp_f32_e32 v121, v121
	v_exp_f32_e32 v122, v122
	v_exp_f32_e32 v123, v123
	v_add_f32_e32 v124, 1.0, v124
	v_add_f32_e32 v125, 1.0, v125
	v_add_f32_e32 v126, 1.0, v126
	v_add_f32_e32 v127, 1.0, v127
	v_add_f32_e32 v120, 1.0, v120
	v_add_f32_e32 v121, 1.0, v121
	v_add_f32_e32 v122, 1.0, v122
	v_add_f32_e32 v123, 1.0, v123
	v_rcp_f32_e32 v124, v124
	v_rcp_f32_e32 v125, v125
	v_rcp_f32_e32 v126, v126
	v_rcp_f32_e32 v127, v127
	v_rcp_f32_e32 v120, v120
	v_rcp_f32_e32 v121, v121
	v_rcp_f32_e32 v122, v122
	v_rcp_f32_e32 v123, v123
	v_lshlrev_b32_e32 v144, 16, v160
	v_and_b32_e32 v145, 0xffff0000, v160
	v_lshlrev_b32_e32 v242, 16, v164
	v_and_b32_e32 v243, 0xffff0000, v164
	v_lshlrev_b32_e32 v146, 16, v161
	v_and_b32_e32 v147, 0xffff0000, v161
	v_lshlrev_b32_e32 v244, 16, v165
	v_and_b32_e32 v245, 0xffff0000, v165
	v_lshlrev_b32_e32 v148, 16, v162
	v_and_b32_e32 v149, 0xffff0000, v162
	v_lshlrev_b32_e32 v246, 16, v166
	v_and_b32_e32 v247, 0xffff0000, v166
	v_lshlrev_b32_e32 v150, 16, v163
	v_and_b32_e32 v151, 0xffff0000, v163
	v_lshlrev_b32_e32 v248, 16, v167
	v_and_b32_e32 v249, 0xffff0000, v167
	v_pk_fma_f32 v[124:125], v[124:125], v[242:243], v[144:145]
	v_pk_fma_f32 v[126:127], v[126:127], v[244:245], v[146:147]
	v_pk_fma_f32 v[120:121], v[120:121], v[246:247], v[148:149]
	v_pk_fma_f32 v[122:123], v[122:123], v[248:249], v[150:151]
	global_store_dwordx4 v[224:225], v[124:127], off
	global_store_dwordx4 v[224:225], v[120:123], off offset:16
	v_pk_mul_f32 v[116:117], v[116:117], v[226:227] op_sel_hi:[1,0]
	v_pk_mul_f32 v[118:119], v[118:119], v[226:227] op_sel_hi:[1,0]
	v_pk_mul_f32 v[112:113], v[112:113], v[226:227] op_sel_hi:[1,0]
	v_pk_mul_f32 v[114:115], v[114:115], v[226:227] op_sel_hi:[1,0]
	v_mul_f32_e32 v116, 0xbfb8aa3b, v116
	v_mul_f32_e32 v117, 0xbfb8aa3b, v117
	v_mul_f32_e32 v118, 0xbfb8aa3b, v118
	v_mul_f32_e32 v119, 0xbfb8aa3b, v119
	v_mul_f32_e32 v112, 0xbfb8aa3b, v112
	v_mul_f32_e32 v113, 0xbfb8aa3b, v113
	v_mul_f32_e32 v114, 0xbfb8aa3b, v114
	v_mul_f32_e32 v115, 0xbfb8aa3b, v115
	v_exp_f32_e32 v116, v116
	v_exp_f32_e32 v117, v117
	v_exp_f32_e32 v118, v118
	v_exp_f32_e32 v119, v119
	v_exp_f32_e32 v112, v112
	v_exp_f32_e32 v113, v113
	v_exp_f32_e32 v114, v114
	v_exp_f32_e32 v115, v115
	v_add_f32_e32 v116, 1.0, v116
	v_add_f32_e32 v117, 1.0, v117
	v_add_f32_e32 v118, 1.0, v118
	v_add_f32_e32 v119, 1.0, v119
	v_add_f32_e32 v112, 1.0, v112
	v_add_f32_e32 v113, 1.0, v113
	v_add_f32_e32 v114, 1.0, v114
	v_add_f32_e32 v115, 1.0, v115
	v_rcp_f32_e32 v116, v116
	v_rcp_f32_e32 v117, v117
	v_rcp_f32_e32 v118, v118
	v_rcp_f32_e32 v119, v119
	v_rcp_f32_e32 v112, v112
	v_rcp_f32_e32 v113, v113
	v_rcp_f32_e32 v114, v114
	v_rcp_f32_e32 v115, v115
	v_lshlrev_b32_e32 v144, 16, v168
	v_and_b32_e32 v145, 0xffff0000, v168
	v_lshlrev_b32_e32 v242, 16, v172
	v_and_b32_e32 v243, 0xffff0000, v172
	v_lshlrev_b32_e32 v146, 16, v169
	v_and_b32_e32 v147, 0xffff0000, v169
	v_lshlrev_b32_e32 v244, 16, v173
	v_and_b32_e32 v245, 0xffff0000, v173
	v_lshlrev_b32_e32 v148, 16, v170
	v_and_b32_e32 v149, 0xffff0000, v170
	v_lshlrev_b32_e32 v246, 16, v174
	v_and_b32_e32 v247, 0xffff0000, v174
	v_lshlrev_b32_e32 v150, 16, v171
	v_and_b32_e32 v151, 0xffff0000, v171
	v_lshlrev_b32_e32 v248, 16, v175
	v_and_b32_e32 v249, 0xffff0000, v175
	v_pk_fma_f32 v[116:117], v[116:117], v[242:243], v[144:145]
	v_pk_fma_f32 v[118:119], v[118:119], v[244:245], v[146:147]
	v_pk_fma_f32 v[112:113], v[112:113], v[246:247], v[148:149]
	v_pk_fma_f32 v[114:115], v[114:115], v[248:249], v[150:151]
	global_store_dwordx4 v[224:225], v[116:119], off offset:512
	global_store_dwordx4 v[224:225], v[112:115], off offset:528
	v_lshl_add_u64 v[224:225], v[224:225], 0, s[50:51]
	global_load_dwordx4 v[160:163], v[250:251], off
	global_load_dwordx4 v[164:167], v[252:253], off nt
	global_load_dwordx4 v[168:171], v[250:251], off offset:256
	global_load_dwordx4 v[172:175], v[252:253], off offset:256 nt
	v_lshl_add_u64 v[250:251], v[250:251], 0, s[28:29]
	v_lshl_add_u64 v[252:253], v[252:253], 0, s[28:29]
	s_waitcnt vmcnt(16)
	v_pk_mul_f32 v[108:109], v[108:109], v[228:229] op_sel_hi:[1,0]
	v_pk_mul_f32 v[110:111], v[110:111], v[228:229] op_sel_hi:[1,0]
	v_pk_mul_f32 v[104:105], v[104:105], v[228:229] op_sel_hi:[1,0]
	v_pk_mul_f32 v[106:107], v[106:107], v[228:229] op_sel_hi:[1,0]
	v_mul_f32_e32 v108, 0xbfb8aa3b, v108
	v_mul_f32_e32 v109, 0xbfb8aa3b, v109
	v_mul_f32_e32 v110, 0xbfb8aa3b, v110
	v_mul_f32_e32 v111, 0xbfb8aa3b, v111
	v_mul_f32_e32 v104, 0xbfb8aa3b, v104
	v_mul_f32_e32 v105, 0xbfb8aa3b, v105
	v_mul_f32_e32 v106, 0xbfb8aa3b, v106
	v_mul_f32_e32 v107, 0xbfb8aa3b, v107
	v_exp_f32_e32 v108, v108
	v_exp_f32_e32 v109, v109
	v_exp_f32_e32 v110, v110
	v_exp_f32_e32 v111, v111
	v_exp_f32_e32 v104, v104
	v_exp_f32_e32 v105, v105
	v_exp_f32_e32 v106, v106
	v_exp_f32_e32 v107, v107
	v_add_f32_e32 v108, 1.0, v108
	v_add_f32_e32 v109, 1.0, v109
	v_add_f32_e32 v110, 1.0, v110
	v_add_f32_e32 v111, 1.0, v111
	v_add_f32_e32 v104, 1.0, v104
	v_add_f32_e32 v105, 1.0, v105
	v_add_f32_e32 v106, 1.0, v106
	v_add_f32_e32 v107, 1.0, v107
	v_rcp_f32_e32 v108, v108
	v_rcp_f32_e32 v109, v109
	v_rcp_f32_e32 v110, v110
	v_rcp_f32_e32 v111, v111
	v_rcp_f32_e32 v104, v104
	v_rcp_f32_e32 v105, v105
	v_rcp_f32_e32 v106, v106
	v_rcp_f32_e32 v107, v107
	v_lshlrev_b32_e32 v144, 16, v176
	v_and_b32_e32 v145, 0xffff0000, v176
	v_lshlrev_b32_e32 v242, 16, v180
	v_and_b32_e32 v243, 0xffff0000, v180
	v_lshlrev_b32_e32 v146, 16, v177
	v_and_b32_e32 v147, 0xffff0000, v177
	v_lshlrev_b32_e32 v244, 16, v181
	v_and_b32_e32 v245, 0xffff0000, v181
	v_lshlrev_b32_e32 v148, 16, v178
	v_and_b32_e32 v149, 0xffff0000, v178
	v_lshlrev_b32_e32 v246, 16, v182
	v_and_b32_e32 v247, 0xffff0000, v182
	v_lshlrev_b32_e32 v150, 16, v179
	v_and_b32_e32 v151, 0xffff0000, v179
	v_lshlrev_b32_e32 v248, 16, v183
	v_and_b32_e32 v249, 0xffff0000, v183
	v_pk_fma_f32 v[108:109], v[108:109], v[242:243], v[144:145]
	v_pk_fma_f32 v[110:111], v[110:111], v[244:245], v[146:147]
	v_pk_fma_f32 v[104:105], v[104:105], v[246:247], v[148:149]
	v_pk_fma_f32 v[106:107], v[106:107], v[248:249], v[150:151]
	global_store_dwordx4 v[224:225], v[108:111], off
	global_store_dwordx4 v[224:225], v[104:107], off offset:16
	v_pk_mul_f32 v[100:101], v[100:101], v[228:229] op_sel_hi:[1,0]
	v_pk_mul_f32 v[102:103], v[102:103], v[228:229] op_sel_hi:[1,0]
	v_pk_mul_f32 v[96:97], v[96:97], v[228:229] op_sel_hi:[1,0]
	v_pk_mul_f32 v[98:99], v[98:99], v[228:229] op_sel_hi:[1,0]
	v_mul_f32_e32 v100, 0xbfb8aa3b, v100
	v_mul_f32_e32 v101, 0xbfb8aa3b, v101
	v_mul_f32_e32 v102, 0xbfb8aa3b, v102
	v_mul_f32_e32 v103, 0xbfb8aa3b, v103
	v_mul_f32_e32 v96, 0xbfb8aa3b, v96
	v_mul_f32_e32 v97, 0xbfb8aa3b, v97
	v_mul_f32_e32 v98, 0xbfb8aa3b, v98
	v_mul_f32_e32 v99, 0xbfb8aa3b, v99
	v_exp_f32_e32 v100, v100
	v_exp_f32_e32 v101, v101
	v_exp_f32_e32 v102, v102
	v_exp_f32_e32 v103, v103
	v_exp_f32_e32 v96, v96
	v_exp_f32_e32 v97, v97
	v_exp_f32_e32 v98, v98
	v_exp_f32_e32 v99, v99
	v_add_f32_e32 v100, 1.0, v100
	v_add_f32_e32 v101, 1.0, v101
	v_add_f32_e32 v102, 1.0, v102
	v_add_f32_e32 v103, 1.0, v103
	v_add_f32_e32 v96, 1.0, v96
	v_add_f32_e32 v97, 1.0, v97
	v_add_f32_e32 v98, 1.0, v98
	v_add_f32_e32 v99, 1.0, v99
	v_rcp_f32_e32 v100, v100
	v_rcp_f32_e32 v101, v101
	v_rcp_f32_e32 v102, v102
	v_rcp_f32_e32 v103, v103
	v_rcp_f32_e32 v96, v96
	v_rcp_f32_e32 v97, v97
	v_rcp_f32_e32 v98, v98
	v_rcp_f32_e32 v99, v99
	v_lshlrev_b32_e32 v144, 16, v184
	v_and_b32_e32 v145, 0xffff0000, v184
	v_lshlrev_b32_e32 v242, 16, v188
	v_and_b32_e32 v243, 0xffff0000, v188
	v_lshlrev_b32_e32 v146, 16, v185
	v_and_b32_e32 v147, 0xffff0000, v185
	v_lshlrev_b32_e32 v244, 16, v189
	v_and_b32_e32 v245, 0xffff0000, v189
	v_lshlrev_b32_e32 v148, 16, v186
	v_and_b32_e32 v149, 0xffff0000, v186
	v_lshlrev_b32_e32 v246, 16, v190
	v_and_b32_e32 v247, 0xffff0000, v190
	v_lshlrev_b32_e32 v150, 16, v187
	v_and_b32_e32 v151, 0xffff0000, v187
	v_lshlrev_b32_e32 v248, 16, v191
	v_and_b32_e32 v249, 0xffff0000, v191
	v_pk_fma_f32 v[100:101], v[100:101], v[242:243], v[144:145]
	v_pk_fma_f32 v[102:103], v[102:103], v[244:245], v[146:147]
	v_pk_fma_f32 v[96:97], v[96:97], v[246:247], v[148:149]
	v_pk_fma_f32 v[98:99], v[98:99], v[248:249], v[150:151]
	global_store_dwordx4 v[224:225], v[100:103], off offset:512
	global_store_dwordx4 v[224:225], v[96:99], off offset:528
	v_lshl_add_u64 v[224:225], v[224:225], 0, s[50:51]
	global_load_dwordx4 v[176:179], v[250:251], off
	global_load_dwordx4 v[180:183], v[252:253], off nt
	global_load_dwordx4 v[184:187], v[250:251], off offset:256
	global_load_dwordx4 v[188:191], v[252:253], off offset:256 nt
	v_lshl_add_u64 v[250:251], v[250:251], 0, s[28:29]
	v_lshl_add_u64 v[252:253], v[252:253], 0, s[28:29]
	v_lshl_add_u32 v144, s17, 8, v152
	v_mov_b32_e32 v145, 0
	v_lshlrev_b64 v[144:145], 6, v[144:145]
	v_and_b32_e32 v146, 24, v154
	v_lshlrev_b32_e32 v146, 1, v146
	v_mov_b32_e32 v147, 0
	v_lshl_add_u64 v[144:145], s[6:7], 0, v[144:145]
	v_lshl_add_u64 v[144:145], v[144:145], 0, v[146:147]
	global_load_dwordx4 v[112:115], v[144:145], off
	global_load_dwordx4 v[116:119], v[144:145], off offset:1024
	global_load_dwordx4 v[120:123], v[144:145], off offset:2048
	global_load_dwordx4 v[124:127], v[144:145], off offset:3072
	v_add_co_u32_e32 v144, vcc, 0x2000, v144
	s_nop 1
	v_addc_co_u32_e32 v145, vcc, 0, v145, vcc
	global_load_dwordx4 v[96:99], v[144:145], off
	global_load_dwordx4 v[100:103], v[144:145], off offset:1024
	global_load_dwordx4 v[104:107], v[144:145], off offset:2048
	global_load_dwordx4 v[108:111], v[144:145], off offset:3072
	s_waitcnt vmcnt(28)
	v_pk_mul_f32 v[92:93], v[92:93], v[230:231] op_sel_hi:[1,0]
	v_pk_mul_f32 v[94:95], v[94:95], v[230:231] op_sel_hi:[1,0]
	v_pk_mul_f32 v[88:89], v[88:89], v[230:231] op_sel_hi:[1,0]
	v_pk_mul_f32 v[90:91], v[90:91], v[230:231] op_sel_hi:[1,0]
	v_mul_f32_e32 v92, 0xbfb8aa3b, v92
	v_mul_f32_e32 v93, 0xbfb8aa3b, v93
	v_mul_f32_e32 v94, 0xbfb8aa3b, v94
	v_mul_f32_e32 v95, 0xbfb8aa3b, v95
	v_mul_f32_e32 v88, 0xbfb8aa3b, v88
	v_mul_f32_e32 v89, 0xbfb8aa3b, v89
	v_mul_f32_e32 v90, 0xbfb8aa3b, v90
	v_mul_f32_e32 v91, 0xbfb8aa3b, v91
	v_exp_f32_e32 v92, v92
	v_exp_f32_e32 v93, v93
	v_exp_f32_e32 v94, v94
	v_exp_f32_e32 v95, v95
	v_exp_f32_e32 v88, v88
	v_exp_f32_e32 v89, v89
	v_exp_f32_e32 v90, v90
	v_exp_f32_e32 v91, v91
	v_add_f32_e32 v92, 1.0, v92
	v_add_f32_e32 v93, 1.0, v93
	v_add_f32_e32 v94, 1.0, v94
	v_add_f32_e32 v95, 1.0, v95
	v_add_f32_e32 v88, 1.0, v88
	v_add_f32_e32 v89, 1.0, v89
	v_add_f32_e32 v90, 1.0, v90
	v_add_f32_e32 v91, 1.0, v91
	v_rcp_f32_e32 v92, v92
	v_rcp_f32_e32 v93, v93
	v_rcp_f32_e32 v94, v94
	v_rcp_f32_e32 v95, v95
	v_rcp_f32_e32 v88, v88
	v_rcp_f32_e32 v89, v89
	v_rcp_f32_e32 v90, v90
	v_rcp_f32_e32 v91, v91
	v_lshlrev_b32_e32 v144, 16, v192
	v_and_b32_e32 v145, 0xffff0000, v192
	v_lshlrev_b32_e32 v242, 16, v196
	v_and_b32_e32 v243, 0xffff0000, v196
	v_lshlrev_b32_e32 v146, 16, v193
	v_and_b32_e32 v147, 0xffff0000, v193
	v_lshlrev_b32_e32 v244, 16, v197
	v_and_b32_e32 v245, 0xffff0000, v197
	v_lshlrev_b32_e32 v148, 16, v194
	v_and_b32_e32 v149, 0xffff0000, v194
	v_lshlrev_b32_e32 v246, 16, v198
	v_and_b32_e32 v247, 0xffff0000, v198
	v_lshlrev_b32_e32 v150, 16, v195
	v_and_b32_e32 v151, 0xffff0000, v195
	v_lshlrev_b32_e32 v248, 16, v199
	v_and_b32_e32 v249, 0xffff0000, v199
	v_pk_fma_f32 v[92:93], v[92:93], v[242:243], v[144:145]
	v_pk_fma_f32 v[94:95], v[94:95], v[244:245], v[146:147]
	v_pk_fma_f32 v[88:89], v[88:89], v[246:247], v[148:149]
	v_pk_fma_f32 v[90:91], v[90:91], v[248:249], v[150:151]
	global_store_dwordx4 v[224:225], v[92:95], off
	global_store_dwordx4 v[224:225], v[88:91], off offset:16
	v_pk_mul_f32 v[84:85], v[84:85], v[230:231] op_sel_hi:[1,0]
	v_pk_mul_f32 v[86:87], v[86:87], v[230:231] op_sel_hi:[1,0]
	v_pk_mul_f32 v[80:81], v[80:81], v[230:231] op_sel_hi:[1,0]
	v_pk_mul_f32 v[82:83], v[82:83], v[230:231] op_sel_hi:[1,0]
	v_mul_f32_e32 v84, 0xbfb8aa3b, v84
	v_mul_f32_e32 v85, 0xbfb8aa3b, v85
	v_mul_f32_e32 v86, 0xbfb8aa3b, v86
	v_mul_f32_e32 v87, 0xbfb8aa3b, v87
	v_mul_f32_e32 v80, 0xbfb8aa3b, v80
	v_mul_f32_e32 v81, 0xbfb8aa3b, v81
	v_mul_f32_e32 v82, 0xbfb8aa3b, v82
	v_mul_f32_e32 v83, 0xbfb8aa3b, v83
	v_exp_f32_e32 v84, v84
	v_exp_f32_e32 v85, v85
	v_exp_f32_e32 v86, v86
	v_exp_f32_e32 v87, v87
	v_exp_f32_e32 v80, v80
	v_exp_f32_e32 v81, v81
	v_exp_f32_e32 v82, v82
	v_exp_f32_e32 v83, v83
	v_add_f32_e32 v84, 1.0, v84
	v_add_f32_e32 v85, 1.0, v85
	v_add_f32_e32 v86, 1.0, v86
	v_add_f32_e32 v87, 1.0, v87
	v_add_f32_e32 v80, 1.0, v80
	v_add_f32_e32 v81, 1.0, v81
	v_add_f32_e32 v82, 1.0, v82
	v_add_f32_e32 v83, 1.0, v83
	v_rcp_f32_e32 v84, v84
	v_rcp_f32_e32 v85, v85
	v_rcp_f32_e32 v86, v86
	v_rcp_f32_e32 v87, v87
	v_rcp_f32_e32 v80, v80
	v_rcp_f32_e32 v81, v81
	v_rcp_f32_e32 v82, v82
	v_rcp_f32_e32 v83, v83
	v_lshlrev_b32_e32 v144, 16, v200
	v_and_b32_e32 v145, 0xffff0000, v200
	v_lshlrev_b32_e32 v242, 16, v204
	v_and_b32_e32 v243, 0xffff0000, v204
	v_lshlrev_b32_e32 v146, 16, v201
	v_and_b32_e32 v147, 0xffff0000, v201
	v_lshlrev_b32_e32 v244, 16, v205
	v_and_b32_e32 v245, 0xffff0000, v205
	v_lshlrev_b32_e32 v148, 16, v202
	v_and_b32_e32 v149, 0xffff0000, v202
	v_lshlrev_b32_e32 v246, 16, v206
	v_and_b32_e32 v247, 0xffff0000, v206
	v_lshlrev_b32_e32 v150, 16, v203
	v_and_b32_e32 v151, 0xffff0000, v203
	v_lshlrev_b32_e32 v248, 16, v207
	v_and_b32_e32 v249, 0xffff0000, v207
	v_pk_fma_f32 v[84:85], v[84:85], v[242:243], v[144:145]
	v_pk_fma_f32 v[86:87], v[86:87], v[244:245], v[146:147]
	v_pk_fma_f32 v[80:81], v[80:81], v[246:247], v[148:149]
	v_pk_fma_f32 v[82:83], v[82:83], v[248:249], v[150:151]
	global_store_dwordx4 v[224:225], v[84:87], off offset:512
	global_store_dwordx4 v[224:225], v[80:83], off offset:528
	v_lshl_add_u64 v[224:225], v[224:225], 0, s[50:51]
	global_load_dwordx4 v[192:195], v[250:251], off
	global_load_dwordx4 v[196:199], v[252:253], off nt
	global_load_dwordx4 v[200:203], v[250:251], off offset:256
	global_load_dwordx4 v[204:207], v[252:253], off offset:256 nt
	v_lshl_add_u64 v[250:251], v[250:251], 0, s[28:29]
	v_lshl_add_u64 v[252:253], v[252:253], 0, s[28:29]
	s_waitcnt vmcnt(32)
	v_pk_mul_f32 v[76:77], v[76:77], v[232:233] op_sel_hi:[1,0]
	v_pk_mul_f32 v[78:79], v[78:79], v[232:233] op_sel_hi:[1,0]
	v_pk_mul_f32 v[72:73], v[72:73], v[232:233] op_sel_hi:[1,0]
	v_pk_mul_f32 v[74:75], v[74:75], v[232:233] op_sel_hi:[1,0]
	v_mul_f32_e32 v76, 0xbfb8aa3b, v76
	v_mul_f32_e32 v77, 0xbfb8aa3b, v77
	v_mul_f32_e32 v78, 0xbfb8aa3b, v78
	v_mul_f32_e32 v79, 0xbfb8aa3b, v79
	v_mul_f32_e32 v72, 0xbfb8aa3b, v72
	v_mul_f32_e32 v73, 0xbfb8aa3b, v73
	v_mul_f32_e32 v74, 0xbfb8aa3b, v74
	v_mul_f32_e32 v75, 0xbfb8aa3b, v75
	v_exp_f32_e32 v76, v76
	v_exp_f32_e32 v77, v77
	v_exp_f32_e32 v78, v78
	v_exp_f32_e32 v79, v79
	v_exp_f32_e32 v72, v72
	v_exp_f32_e32 v73, v73
	v_exp_f32_e32 v74, v74
	v_exp_f32_e32 v75, v75
	v_add_f32_e32 v76, 1.0, v76
	v_add_f32_e32 v77, 1.0, v77
	v_add_f32_e32 v78, 1.0, v78
	v_add_f32_e32 v79, 1.0, v79
	v_add_f32_e32 v72, 1.0, v72
	v_add_f32_e32 v73, 1.0, v73
	v_add_f32_e32 v74, 1.0, v74
	v_add_f32_e32 v75, 1.0, v75
	v_rcp_f32_e32 v76, v76
	v_rcp_f32_e32 v77, v77
	v_rcp_f32_e32 v78, v78
	v_rcp_f32_e32 v79, v79
	v_rcp_f32_e32 v72, v72
	v_rcp_f32_e32 v73, v73
	v_rcp_f32_e32 v74, v74
	v_rcp_f32_e32 v75, v75
	v_lshlrev_b32_e32 v144, 16, v208
	v_and_b32_e32 v145, 0xffff0000, v208
	v_lshlrev_b32_e32 v242, 16, v212
	v_and_b32_e32 v243, 0xffff0000, v212
	v_lshlrev_b32_e32 v146, 16, v209
	v_and_b32_e32 v147, 0xffff0000, v209
	v_lshlrev_b32_e32 v244, 16, v213
	v_and_b32_e32 v245, 0xffff0000, v213
	v_lshlrev_b32_e32 v148, 16, v210
	v_and_b32_e32 v149, 0xffff0000, v210
	v_lshlrev_b32_e32 v246, 16, v214
	v_and_b32_e32 v247, 0xffff0000, v214
	v_lshlrev_b32_e32 v150, 16, v211
	v_and_b32_e32 v151, 0xffff0000, v211
	v_lshlrev_b32_e32 v248, 16, v215
	v_and_b32_e32 v249, 0xffff0000, v215
	v_pk_fma_f32 v[76:77], v[76:77], v[242:243], v[144:145]
	v_pk_fma_f32 v[78:79], v[78:79], v[244:245], v[146:147]
	v_pk_fma_f32 v[72:73], v[72:73], v[246:247], v[148:149]
	v_pk_fma_f32 v[74:75], v[74:75], v[248:249], v[150:151]
	global_store_dwordx4 v[224:225], v[76:79], off
	global_store_dwordx4 v[224:225], v[72:75], off offset:16
	v_pk_mul_f32 v[68:69], v[68:69], v[232:233] op_sel_hi:[1,0]
	v_pk_mul_f32 v[70:71], v[70:71], v[232:233] op_sel_hi:[1,0]
	v_pk_mul_f32 v[64:65], v[64:65], v[232:233] op_sel_hi:[1,0]
	v_pk_mul_f32 v[66:67], v[66:67], v[232:233] op_sel_hi:[1,0]
	v_mul_f32_e32 v68, 0xbfb8aa3b, v68
	v_mul_f32_e32 v69, 0xbfb8aa3b, v69
	v_mul_f32_e32 v70, 0xbfb8aa3b, v70
	v_mul_f32_e32 v71, 0xbfb8aa3b, v71
	v_mul_f32_e32 v64, 0xbfb8aa3b, v64
	v_mul_f32_e32 v65, 0xbfb8aa3b, v65
	v_mul_f32_e32 v66, 0xbfb8aa3b, v66
	v_mul_f32_e32 v67, 0xbfb8aa3b, v67
	v_exp_f32_e32 v68, v68
	v_exp_f32_e32 v69, v69
	v_exp_f32_e32 v70, v70
	v_exp_f32_e32 v71, v71
	v_exp_f32_e32 v64, v64
	v_exp_f32_e32 v65, v65
	v_exp_f32_e32 v66, v66
	v_exp_f32_e32 v67, v67
	v_add_f32_e32 v68, 1.0, v68
	v_add_f32_e32 v69, 1.0, v69
	v_add_f32_e32 v70, 1.0, v70
	v_add_f32_e32 v71, 1.0, v71
	v_add_f32_e32 v64, 1.0, v64
	v_add_f32_e32 v65, 1.0, v65
	v_add_f32_e32 v66, 1.0, v66
	v_add_f32_e32 v67, 1.0, v67
	v_rcp_f32_e32 v68, v68
	v_rcp_f32_e32 v69, v69
	v_rcp_f32_e32 v70, v70
	v_rcp_f32_e32 v71, v71
	v_rcp_f32_e32 v64, v64
	v_rcp_f32_e32 v65, v65
	v_rcp_f32_e32 v66, v66
	v_rcp_f32_e32 v67, v67
	v_lshlrev_b32_e32 v144, 16, v216
	v_and_b32_e32 v145, 0xffff0000, v216
	v_lshlrev_b32_e32 v242, 16, v220
	v_and_b32_e32 v243, 0xffff0000, v220
	v_lshlrev_b32_e32 v146, 16, v217
	v_and_b32_e32 v147, 0xffff0000, v217
	v_lshlrev_b32_e32 v244, 16, v221
	v_and_b32_e32 v245, 0xffff0000, v221
	v_lshlrev_b32_e32 v148, 16, v218
	v_and_b32_e32 v149, 0xffff0000, v218
	v_lshlrev_b32_e32 v246, 16, v222
	v_and_b32_e32 v247, 0xffff0000, v222
	v_lshlrev_b32_e32 v150, 16, v219
	v_and_b32_e32 v151, 0xffff0000, v219
	v_lshlrev_b32_e32 v248, 16, v223
	v_and_b32_e32 v249, 0xffff0000, v223
	v_pk_fma_f32 v[68:69], v[68:69], v[242:243], v[144:145]
	v_pk_fma_f32 v[70:71], v[70:71], v[244:245], v[146:147]
	v_pk_fma_f32 v[64:65], v[64:65], v[246:247], v[148:149]
	v_pk_fma_f32 v[66:67], v[66:67], v[248:249], v[150:151]
	global_store_dwordx4 v[224:225], v[68:71], off offset:512
	global_store_dwordx4 v[224:225], v[64:67], off offset:528
	v_lshl_add_u64 v[224:225], v[224:225], 0, s[52:53]
	global_load_dwordx4 v[208:211], v[250:251], off
	global_load_dwordx4 v[212:215], v[252:253], off nt
	global_load_dwordx4 v[216:219], v[250:251], off offset:256
	global_load_dwordx4 v[220:223], v[252:253], off offset:256 nt
	s_waitcnt vmcnt(32)
	v_pk_mul_f32 v[60:61], v[60:61], v[234:235] op_sel_hi:[1,0]
	v_pk_mul_f32 v[62:63], v[62:63], v[234:235] op_sel_hi:[1,0]
	v_pk_mul_f32 v[56:57], v[56:57], v[234:235] op_sel_hi:[1,0]
	v_pk_mul_f32 v[58:59], v[58:59], v[234:235] op_sel_hi:[1,0]
	v_mul_f32_e32 v60, 0xbfb8aa3b, v60
	v_mul_f32_e32 v61, 0xbfb8aa3b, v61
	v_mul_f32_e32 v62, 0xbfb8aa3b, v62
	v_mul_f32_e32 v63, 0xbfb8aa3b, v63
	v_mul_f32_e32 v56, 0xbfb8aa3b, v56
	v_mul_f32_e32 v57, 0xbfb8aa3b, v57
	v_mul_f32_e32 v58, 0xbfb8aa3b, v58
	v_mul_f32_e32 v59, 0xbfb8aa3b, v59
	v_exp_f32_e32 v60, v60
	v_exp_f32_e32 v61, v61
	v_exp_f32_e32 v62, v62
	v_exp_f32_e32 v63, v63
	v_exp_f32_e32 v56, v56
	v_exp_f32_e32 v57, v57
	v_exp_f32_e32 v58, v58
	v_exp_f32_e32 v59, v59
	v_add_f32_e32 v60, 1.0, v60
	v_add_f32_e32 v61, 1.0, v61
	v_add_f32_e32 v62, 1.0, v62
	v_add_f32_e32 v63, 1.0, v63
	v_add_f32_e32 v56, 1.0, v56
	v_add_f32_e32 v57, 1.0, v57
	v_add_f32_e32 v58, 1.0, v58
	v_add_f32_e32 v59, 1.0, v59
	v_rcp_f32_e32 v60, v60
	v_rcp_f32_e32 v61, v61
	v_rcp_f32_e32 v62, v62
	v_rcp_f32_e32 v63, v63
	v_rcp_f32_e32 v56, v56
	v_rcp_f32_e32 v57, v57
	v_rcp_f32_e32 v58, v58
	v_rcp_f32_e32 v59, v59
	v_lshlrev_b32_e32 v144, 16, v160
	v_and_b32_e32 v145, 0xffff0000, v160
	v_lshlrev_b32_e32 v242, 16, v164
	v_and_b32_e32 v243, 0xffff0000, v164
	v_lshlrev_b32_e32 v146, 16, v161
	v_and_b32_e32 v147, 0xffff0000, v161
	v_lshlrev_b32_e32 v244, 16, v165
	v_and_b32_e32 v245, 0xffff0000, v165
	v_lshlrev_b32_e32 v148, 16, v162
	v_and_b32_e32 v149, 0xffff0000, v162
	v_lshlrev_b32_e32 v246, 16, v166
	v_and_b32_e32 v247, 0xffff0000, v166
	v_lshlrev_b32_e32 v150, 16, v163
	v_and_b32_e32 v151, 0xffff0000, v163
	v_lshlrev_b32_e32 v248, 16, v167
	v_and_b32_e32 v249, 0xffff0000, v167
	v_pk_fma_f32 v[60:61], v[60:61], v[242:243], v[144:145]
	v_pk_fma_f32 v[62:63], v[62:63], v[244:245], v[146:147]
	v_pk_fma_f32 v[56:57], v[56:57], v[246:247], v[148:149]
	v_pk_fma_f32 v[58:59], v[58:59], v[248:249], v[150:151]
	global_store_dwordx4 v[224:225], v[60:63], off
	global_store_dwordx4 v[224:225], v[56:59], off offset:16
	v_pk_mul_f32 v[52:53], v[52:53], v[234:235] op_sel_hi:[1,0]
	v_pk_mul_f32 v[54:55], v[54:55], v[234:235] op_sel_hi:[1,0]
	v_pk_mul_f32 v[48:49], v[48:49], v[234:235] op_sel_hi:[1,0]
	v_pk_mul_f32 v[50:51], v[50:51], v[234:235] op_sel_hi:[1,0]
	v_mul_f32_e32 v52, 0xbfb8aa3b, v52
	v_mul_f32_e32 v53, 0xbfb8aa3b, v53
	v_mul_f32_e32 v54, 0xbfb8aa3b, v54
	v_mul_f32_e32 v55, 0xbfb8aa3b, v55
	v_mul_f32_e32 v48, 0xbfb8aa3b, v48
	v_mul_f32_e32 v49, 0xbfb8aa3b, v49
	v_mul_f32_e32 v50, 0xbfb8aa3b, v50
	v_mul_f32_e32 v51, 0xbfb8aa3b, v51
	v_exp_f32_e32 v52, v52
	v_exp_f32_e32 v53, v53
	v_exp_f32_e32 v54, v54
	v_exp_f32_e32 v55, v55
	v_exp_f32_e32 v48, v48
	v_exp_f32_e32 v49, v49
	v_exp_f32_e32 v50, v50
	v_exp_f32_e32 v51, v51
	v_add_f32_e32 v52, 1.0, v52
	v_add_f32_e32 v53, 1.0, v53
	v_add_f32_e32 v54, 1.0, v54
	v_add_f32_e32 v55, 1.0, v55
	v_add_f32_e32 v48, 1.0, v48
	v_add_f32_e32 v49, 1.0, v49
	v_add_f32_e32 v50, 1.0, v50
	v_add_f32_e32 v51, 1.0, v51
	v_rcp_f32_e32 v52, v52
	v_rcp_f32_e32 v53, v53
	v_rcp_f32_e32 v54, v54
	v_rcp_f32_e32 v55, v55
	v_rcp_f32_e32 v48, v48
	v_rcp_f32_e32 v49, v49
	v_rcp_f32_e32 v50, v50
	v_rcp_f32_e32 v51, v51
	v_lshlrev_b32_e32 v144, 16, v168
	v_and_b32_e32 v145, 0xffff0000, v168
	v_lshlrev_b32_e32 v242, 16, v172
	v_and_b32_e32 v243, 0xffff0000, v172
	v_lshlrev_b32_e32 v146, 16, v169
	v_and_b32_e32 v147, 0xffff0000, v169
	v_lshlrev_b32_e32 v244, 16, v173
	v_and_b32_e32 v245, 0xffff0000, v173
	v_lshlrev_b32_e32 v148, 16, v170
	v_and_b32_e32 v149, 0xffff0000, v170
	v_lshlrev_b32_e32 v246, 16, v174
	v_and_b32_e32 v247, 0xffff0000, v174
	v_lshlrev_b32_e32 v150, 16, v171
	v_and_b32_e32 v151, 0xffff0000, v171
	v_lshlrev_b32_e32 v248, 16, v175
	v_and_b32_e32 v249, 0xffff0000, v175
	v_pk_fma_f32 v[52:53], v[52:53], v[242:243], v[144:145]
	v_pk_fma_f32 v[54:55], v[54:55], v[244:245], v[146:147]
	v_pk_fma_f32 v[48:49], v[48:49], v[246:247], v[148:149]
	v_pk_fma_f32 v[50:51], v[50:51], v[248:249], v[150:151]
	global_store_dwordx4 v[224:225], v[52:55], off offset:512
	global_store_dwordx4 v[224:225], v[48:51], off offset:528
	v_lshl_add_u64 v[224:225], v[224:225], 0, s[50:51]
	s_waitcnt vmcnt(28)
	v_pk_mul_f32 v[44:45], v[44:45], v[236:237] op_sel_hi:[1,0]
	v_pk_mul_f32 v[46:47], v[46:47], v[236:237] op_sel_hi:[1,0]
	v_pk_mul_f32 v[40:41], v[40:41], v[236:237] op_sel_hi:[1,0]
	v_pk_mul_f32 v[42:43], v[42:43], v[236:237] op_sel_hi:[1,0]
	v_mul_f32_e32 v44, 0xbfb8aa3b, v44
	v_mul_f32_e32 v45, 0xbfb8aa3b, v45
	v_mul_f32_e32 v46, 0xbfb8aa3b, v46
	v_mul_f32_e32 v47, 0xbfb8aa3b, v47
	v_mul_f32_e32 v40, 0xbfb8aa3b, v40
	v_mul_f32_e32 v41, 0xbfb8aa3b, v41
	v_mul_f32_e32 v42, 0xbfb8aa3b, v42
	v_mul_f32_e32 v43, 0xbfb8aa3b, v43
	v_exp_f32_e32 v44, v44
	v_exp_f32_e32 v45, v45
	v_exp_f32_e32 v46, v46
	v_exp_f32_e32 v47, v47
	v_exp_f32_e32 v40, v40
	v_exp_f32_e32 v41, v41
	v_exp_f32_e32 v42, v42
	v_exp_f32_e32 v43, v43
	v_add_f32_e32 v44, 1.0, v44
	v_add_f32_e32 v45, 1.0, v45
	v_add_f32_e32 v46, 1.0, v46
	v_add_f32_e32 v47, 1.0, v47
	v_add_f32_e32 v40, 1.0, v40
	v_add_f32_e32 v41, 1.0, v41
	v_add_f32_e32 v42, 1.0, v42
	v_add_f32_e32 v43, 1.0, v43
	v_rcp_f32_e32 v44, v44
	v_rcp_f32_e32 v45, v45
	v_rcp_f32_e32 v46, v46
	v_rcp_f32_e32 v47, v47
	v_rcp_f32_e32 v40, v40
	v_rcp_f32_e32 v41, v41
	v_rcp_f32_e32 v42, v42
	v_rcp_f32_e32 v43, v43
	v_lshlrev_b32_e32 v144, 16, v176
	v_and_b32_e32 v145, 0xffff0000, v176
	v_lshlrev_b32_e32 v242, 16, v180
	v_and_b32_e32 v243, 0xffff0000, v180
	v_lshlrev_b32_e32 v146, 16, v177
	v_and_b32_e32 v147, 0xffff0000, v177
	v_lshlrev_b32_e32 v244, 16, v181
	v_and_b32_e32 v245, 0xffff0000, v181
	v_lshlrev_b32_e32 v148, 16, v178
	v_and_b32_e32 v149, 0xffff0000, v178
	v_lshlrev_b32_e32 v246, 16, v182
	v_and_b32_e32 v247, 0xffff0000, v182
	v_lshlrev_b32_e32 v150, 16, v179
	v_and_b32_e32 v151, 0xffff0000, v179
	v_lshlrev_b32_e32 v248, 16, v183
	v_and_b32_e32 v249, 0xffff0000, v183
	v_pk_fma_f32 v[44:45], v[44:45], v[242:243], v[144:145]
	v_pk_fma_f32 v[46:47], v[46:47], v[244:245], v[146:147]
	v_pk_fma_f32 v[40:41], v[40:41], v[246:247], v[148:149]
	v_pk_fma_f32 v[42:43], v[42:43], v[248:249], v[150:151]
	global_store_dwordx4 v[224:225], v[44:47], off
	global_store_dwordx4 v[224:225], v[40:43], off offset:16
	v_pk_mul_f32 v[36:37], v[36:37], v[236:237] op_sel_hi:[1,0]
	v_pk_mul_f32 v[38:39], v[38:39], v[236:237] op_sel_hi:[1,0]
	v_pk_mul_f32 v[32:33], v[32:33], v[236:237] op_sel_hi:[1,0]
	v_pk_mul_f32 v[34:35], v[34:35], v[236:237] op_sel_hi:[1,0]
	v_mul_f32_e32 v36, 0xbfb8aa3b, v36
	v_mul_f32_e32 v37, 0xbfb8aa3b, v37
	v_mul_f32_e32 v38, 0xbfb8aa3b, v38
	v_mul_f32_e32 v39, 0xbfb8aa3b, v39
	v_mul_f32_e32 v32, 0xbfb8aa3b, v32
	v_mul_f32_e32 v33, 0xbfb8aa3b, v33
	v_mul_f32_e32 v34, 0xbfb8aa3b, v34
	v_mul_f32_e32 v35, 0xbfb8aa3b, v35
	v_exp_f32_e32 v36, v36
	v_exp_f32_e32 v37, v37
	v_exp_f32_e32 v38, v38
	v_exp_f32_e32 v39, v39
	v_exp_f32_e32 v32, v32
	v_exp_f32_e32 v33, v33
	v_exp_f32_e32 v34, v34
	v_exp_f32_e32 v35, v35
	v_add_f32_e32 v36, 1.0, v36
	v_add_f32_e32 v37, 1.0, v37
	v_add_f32_e32 v38, 1.0, v38
	v_add_f32_e32 v39, 1.0, v39
	v_add_f32_e32 v32, 1.0, v32
	v_add_f32_e32 v33, 1.0, v33
	v_add_f32_e32 v34, 1.0, v34
	v_add_f32_e32 v35, 1.0, v35
	v_rcp_f32_e32 v36, v36
	v_rcp_f32_e32 v37, v37
	v_rcp_f32_e32 v38, v38
	v_rcp_f32_e32 v39, v39
	v_rcp_f32_e32 v32, v32
	v_rcp_f32_e32 v33, v33
	v_rcp_f32_e32 v34, v34
	v_rcp_f32_e32 v35, v35
	v_lshlrev_b32_e32 v144, 16, v184
	v_and_b32_e32 v145, 0xffff0000, v184
	v_lshlrev_b32_e32 v242, 16, v188
	v_and_b32_e32 v243, 0xffff0000, v188
	v_lshlrev_b32_e32 v146, 16, v185
	v_and_b32_e32 v147, 0xffff0000, v185
	v_lshlrev_b32_e32 v244, 16, v189
	v_and_b32_e32 v245, 0xffff0000, v189
	v_lshlrev_b32_e32 v148, 16, v186
	v_and_b32_e32 v149, 0xffff0000, v186
	v_lshlrev_b32_e32 v246, 16, v190
	v_and_b32_e32 v247, 0xffff0000, v190
	v_lshlrev_b32_e32 v150, 16, v187
	v_and_b32_e32 v151, 0xffff0000, v187
	v_lshlrev_b32_e32 v248, 16, v191
	v_and_b32_e32 v249, 0xffff0000, v191
	v_pk_fma_f32 v[36:37], v[36:37], v[242:243], v[144:145]
	v_pk_fma_f32 v[38:39], v[38:39], v[244:245], v[146:147]
	v_pk_fma_f32 v[32:33], v[32:33], v[246:247], v[148:149]
	v_pk_fma_f32 v[34:35], v[34:35], v[248:249], v[150:151]
	global_store_dwordx4 v[224:225], v[36:39], off offset:512
	global_store_dwordx4 v[224:225], v[32:35], off offset:528
	v_lshl_add_u64 v[224:225], v[224:225], 0, s[50:51]
	s_waitcnt vmcnt(16)
	v_pk_mul_f32 v[28:29], v[28:29], v[238:239] op_sel_hi:[1,0]
	v_pk_mul_f32 v[30:31], v[30:31], v[238:239] op_sel_hi:[1,0]
	v_pk_mul_f32 v[24:25], v[24:25], v[238:239] op_sel_hi:[1,0]
	v_pk_mul_f32 v[26:27], v[26:27], v[238:239] op_sel_hi:[1,0]
	v_mul_f32_e32 v28, 0xbfb8aa3b, v28
	v_mul_f32_e32 v29, 0xbfb8aa3b, v29
	v_mul_f32_e32 v30, 0xbfb8aa3b, v30
	v_mul_f32_e32 v31, 0xbfb8aa3b, v31
	v_mul_f32_e32 v24, 0xbfb8aa3b, v24
	v_mul_f32_e32 v25, 0xbfb8aa3b, v25
	v_mul_f32_e32 v26, 0xbfb8aa3b, v26
	v_mul_f32_e32 v27, 0xbfb8aa3b, v27
	v_exp_f32_e32 v28, v28
	v_exp_f32_e32 v29, v29
	v_exp_f32_e32 v30, v30
	v_exp_f32_e32 v31, v31
	v_exp_f32_e32 v24, v24
	v_exp_f32_e32 v25, v25
	v_exp_f32_e32 v26, v26
	v_exp_f32_e32 v27, v27
	v_add_f32_e32 v28, 1.0, v28
	v_add_f32_e32 v29, 1.0, v29
	v_add_f32_e32 v30, 1.0, v30
	v_add_f32_e32 v31, 1.0, v31
	v_add_f32_e32 v24, 1.0, v24
	v_add_f32_e32 v25, 1.0, v25
	v_add_f32_e32 v26, 1.0, v26
	v_add_f32_e32 v27, 1.0, v27
	v_rcp_f32_e32 v28, v28
	v_rcp_f32_e32 v29, v29
	v_rcp_f32_e32 v30, v30
	v_rcp_f32_e32 v31, v31
	v_rcp_f32_e32 v24, v24
	v_rcp_f32_e32 v25, v25
	v_rcp_f32_e32 v26, v26
	v_rcp_f32_e32 v27, v27
	v_lshlrev_b32_e32 v144, 16, v192
	v_and_b32_e32 v145, 0xffff0000, v192
	v_lshlrev_b32_e32 v242, 16, v196
	v_and_b32_e32 v243, 0xffff0000, v196
	v_lshlrev_b32_e32 v146, 16, v193
	v_and_b32_e32 v147, 0xffff0000, v193
	v_lshlrev_b32_e32 v244, 16, v197
	v_and_b32_e32 v245, 0xffff0000, v197
	v_lshlrev_b32_e32 v148, 16, v194
	v_and_b32_e32 v149, 0xffff0000, v194
	v_lshlrev_b32_e32 v246, 16, v198
	v_and_b32_e32 v247, 0xffff0000, v198
	v_lshlrev_b32_e32 v150, 16, v195
	v_and_b32_e32 v151, 0xffff0000, v195
	v_lshlrev_b32_e32 v248, 16, v199
	v_and_b32_e32 v249, 0xffff0000, v199
	v_pk_fma_f32 v[28:29], v[28:29], v[242:243], v[144:145]
	v_pk_fma_f32 v[30:31], v[30:31], v[244:245], v[146:147]
	v_pk_fma_f32 v[24:25], v[24:25], v[246:247], v[148:149]
	v_pk_fma_f32 v[26:27], v[26:27], v[248:249], v[150:151]
	global_store_dwordx4 v[224:225], v[28:31], off
	global_store_dwordx4 v[224:225], v[24:27], off offset:16
	v_pk_mul_f32 v[20:21], v[20:21], v[238:239] op_sel_hi:[1,0]
	v_pk_mul_f32 v[22:23], v[22:23], v[238:239] op_sel_hi:[1,0]
	v_pk_mul_f32 v[16:17], v[16:17], v[238:239] op_sel_hi:[1,0]
	v_pk_mul_f32 v[18:19], v[18:19], v[238:239] op_sel_hi:[1,0]
	v_mul_f32_e32 v20, 0xbfb8aa3b, v20
	v_mul_f32_e32 v21, 0xbfb8aa3b, v21
	v_mul_f32_e32 v22, 0xbfb8aa3b, v22
	v_mul_f32_e32 v23, 0xbfb8aa3b, v23
	v_mul_f32_e32 v16, 0xbfb8aa3b, v16
	v_mul_f32_e32 v17, 0xbfb8aa3b, v17
	v_mul_f32_e32 v18, 0xbfb8aa3b, v18
	v_mul_f32_e32 v19, 0xbfb8aa3b, v19
	v_exp_f32_e32 v20, v20
	v_exp_f32_e32 v21, v21
	v_exp_f32_e32 v22, v22
	v_exp_f32_e32 v23, v23
	v_exp_f32_e32 v16, v16
	v_exp_f32_e32 v17, v17
	v_exp_f32_e32 v18, v18
	v_exp_f32_e32 v19, v19
	v_add_f32_e32 v20, 1.0, v20
	v_add_f32_e32 v21, 1.0, v21
	v_add_f32_e32 v22, 1.0, v22
	v_add_f32_e32 v23, 1.0, v23
	v_add_f32_e32 v16, 1.0, v16
	v_add_f32_e32 v17, 1.0, v17
	v_add_f32_e32 v18, 1.0, v18
	v_add_f32_e32 v19, 1.0, v19
	v_rcp_f32_e32 v20, v20
	v_rcp_f32_e32 v21, v21
	v_rcp_f32_e32 v22, v22
	v_rcp_f32_e32 v23, v23
	v_rcp_f32_e32 v16, v16
	v_rcp_f32_e32 v17, v17
	v_rcp_f32_e32 v18, v18
	v_rcp_f32_e32 v19, v19
	v_lshlrev_b32_e32 v144, 16, v200
	v_and_b32_e32 v145, 0xffff0000, v200
	v_lshlrev_b32_e32 v242, 16, v204
	v_and_b32_e32 v243, 0xffff0000, v204
	v_lshlrev_b32_e32 v146, 16, v201
	v_and_b32_e32 v147, 0xffff0000, v201
	v_lshlrev_b32_e32 v244, 16, v205
	v_and_b32_e32 v245, 0xffff0000, v205
	v_lshlrev_b32_e32 v148, 16, v202
	v_and_b32_e32 v149, 0xffff0000, v202
	v_lshlrev_b32_e32 v246, 16, v206
	v_and_b32_e32 v247, 0xffff0000, v206
	v_lshlrev_b32_e32 v150, 16, v203
	v_and_b32_e32 v151, 0xffff0000, v203
	v_lshlrev_b32_e32 v248, 16, v207
	v_and_b32_e32 v249, 0xffff0000, v207
	v_pk_fma_f32 v[20:21], v[20:21], v[242:243], v[144:145]
	v_pk_fma_f32 v[22:23], v[22:23], v[244:245], v[146:147]
	v_pk_fma_f32 v[16:17], v[16:17], v[246:247], v[148:149]
	v_pk_fma_f32 v[18:19], v[18:19], v[248:249], v[150:151]
	global_store_dwordx4 v[224:225], v[20:23], off offset:512
	global_store_dwordx4 v[224:225], v[16:19], off offset:528
	v_lshl_add_u64 v[224:225], v[224:225], 0, s[50:51]
	s_waitcnt vmcnt(12)
	v_pk_mul_f32 v[12:13], v[12:13], v[240:241] op_sel_hi:[1,0]
	v_pk_mul_f32 v[14:15], v[14:15], v[240:241] op_sel_hi:[1,0]
	v_pk_mul_f32 v[8:9], v[8:9], v[240:241] op_sel_hi:[1,0]
	v_pk_mul_f32 v[10:11], v[10:11], v[240:241] op_sel_hi:[1,0]
	v_mul_f32_e32 v12, 0xbfb8aa3b, v12
	v_mul_f32_e32 v13, 0xbfb8aa3b, v13
	v_mul_f32_e32 v14, 0xbfb8aa3b, v14
	v_mul_f32_e32 v15, 0xbfb8aa3b, v15
	v_mul_f32_e32 v8, 0xbfb8aa3b, v8
	v_mul_f32_e32 v9, 0xbfb8aa3b, v9
	v_mul_f32_e32 v10, 0xbfb8aa3b, v10
	v_mul_f32_e32 v11, 0xbfb8aa3b, v11
	v_exp_f32_e32 v12, v12
	v_exp_f32_e32 v13, v13
	v_exp_f32_e32 v14, v14
	v_exp_f32_e32 v15, v15
	v_exp_f32_e32 v8, v8
	v_exp_f32_e32 v9, v9
	v_exp_f32_e32 v10, v10
	v_exp_f32_e32 v11, v11
	v_add_f32_e32 v12, 1.0, v12
	v_add_f32_e32 v13, 1.0, v13
	v_add_f32_e32 v14, 1.0, v14
	v_add_f32_e32 v15, 1.0, v15
	v_add_f32_e32 v8, 1.0, v8
	v_add_f32_e32 v9, 1.0, v9
	v_add_f32_e32 v10, 1.0, v10
	v_add_f32_e32 v11, 1.0, v11
	v_rcp_f32_e32 v12, v12
	v_rcp_f32_e32 v13, v13
	v_rcp_f32_e32 v14, v14
	v_rcp_f32_e32 v15, v15
	v_rcp_f32_e32 v8, v8
	v_rcp_f32_e32 v9, v9
	v_rcp_f32_e32 v10, v10
	v_rcp_f32_e32 v11, v11
	v_lshlrev_b32_e32 v144, 16, v208
	v_and_b32_e32 v145, 0xffff0000, v208
	v_lshlrev_b32_e32 v242, 16, v212
	v_and_b32_e32 v243, 0xffff0000, v212
	v_lshlrev_b32_e32 v146, 16, v209
	v_and_b32_e32 v147, 0xffff0000, v209
	v_lshlrev_b32_e32 v244, 16, v213
	v_and_b32_e32 v245, 0xffff0000, v213
	v_lshlrev_b32_e32 v148, 16, v210
	v_and_b32_e32 v149, 0xffff0000, v210
	v_lshlrev_b32_e32 v246, 16, v214
	v_and_b32_e32 v247, 0xffff0000, v214
	v_lshlrev_b32_e32 v150, 16, v211
	v_and_b32_e32 v151, 0xffff0000, v211
	v_lshlrev_b32_e32 v248, 16, v215
	v_and_b32_e32 v249, 0xffff0000, v215
	v_pk_fma_f32 v[12:13], v[12:13], v[242:243], v[144:145]
	v_pk_fma_f32 v[14:15], v[14:15], v[244:245], v[146:147]
	v_pk_fma_f32 v[8:9], v[8:9], v[246:247], v[148:149]
	v_pk_fma_f32 v[10:11], v[10:11], v[248:249], v[150:151]
	global_store_dwordx4 v[224:225], v[12:15], off
	global_store_dwordx4 v[224:225], v[8:11], off offset:16
	v_pk_mul_f32 v[4:5], v[4:5], v[240:241] op_sel_hi:[1,0]
	v_pk_mul_f32 v[6:7], v[6:7], v[240:241] op_sel_hi:[1,0]
	v_pk_mul_f32 v[0:1], v[0:1], v[240:241] op_sel_hi:[1,0]
	v_pk_mul_f32 v[2:3], v[2:3], v[240:241] op_sel_hi:[1,0]
	v_mul_f32_e32 v4, 0xbfb8aa3b, v4
	v_mul_f32_e32 v5, 0xbfb8aa3b, v5
	v_mul_f32_e32 v6, 0xbfb8aa3b, v6
	v_mul_f32_e32 v7, 0xbfb8aa3b, v7
	v_mul_f32_e32 v0, 0xbfb8aa3b, v0
	v_mul_f32_e32 v1, 0xbfb8aa3b, v1
	v_mul_f32_e32 v2, 0xbfb8aa3b, v2
	v_mul_f32_e32 v3, 0xbfb8aa3b, v3
	v_exp_f32_e32 v4, v4
	v_exp_f32_e32 v5, v5
	v_exp_f32_e32 v6, v6
	v_exp_f32_e32 v7, v7
	v_exp_f32_e32 v0, v0
	v_exp_f32_e32 v1, v1
	v_exp_f32_e32 v2, v2
	v_exp_f32_e32 v3, v3
	v_add_f32_e32 v4, 1.0, v4
	v_add_f32_e32 v5, 1.0, v5
	v_add_f32_e32 v6, 1.0, v6
	v_add_f32_e32 v7, 1.0, v7
	v_add_f32_e32 v0, 1.0, v0
	v_add_f32_e32 v1, 1.0, v1
	v_add_f32_e32 v2, 1.0, v2
	v_add_f32_e32 v3, 1.0, v3
	v_rcp_f32_e32 v4, v4
	v_rcp_f32_e32 v5, v5
	v_rcp_f32_e32 v6, v6
	v_rcp_f32_e32 v7, v7
	v_rcp_f32_e32 v0, v0
	v_rcp_f32_e32 v1, v1
	v_rcp_f32_e32 v2, v2
	v_rcp_f32_e32 v3, v3
	v_lshlrev_b32_e32 v144, 16, v216
	v_and_b32_e32 v145, 0xffff0000, v216
	v_lshlrev_b32_e32 v242, 16, v220
	v_and_b32_e32 v243, 0xffff0000, v220
	v_lshlrev_b32_e32 v146, 16, v217
	v_and_b32_e32 v147, 0xffff0000, v217
	v_lshlrev_b32_e32 v244, 16, v221
	v_and_b32_e32 v245, 0xffff0000, v221
	v_lshlrev_b32_e32 v148, 16, v218
	v_and_b32_e32 v149, 0xffff0000, v218
	v_lshlrev_b32_e32 v246, 16, v222
	v_and_b32_e32 v247, 0xffff0000, v222
	v_lshlrev_b32_e32 v150, 16, v219
	v_and_b32_e32 v151, 0xffff0000, v219
	v_lshlrev_b32_e32 v248, 16, v223
	v_and_b32_e32 v249, 0xffff0000, v223
	v_pk_fma_f32 v[4:5], v[4:5], v[242:243], v[144:145]
	v_pk_fma_f32 v[6:7], v[6:7], v[244:245], v[146:147]
	v_pk_fma_f32 v[0:1], v[0:1], v[246:247], v[148:149]
	v_pk_fma_f32 v[2:3], v[2:3], v[248:249], v[150:151]
	global_store_dwordx4 v[224:225], v[4:7], off offset:512
	global_store_dwordx4 v[224:225], v[0:3], off offset:528
	v_add_f32_e32 v112, v112, v113
	v_add_f32_e32 v116, v116, v117
	v_add_f32_e32 v120, v120, v121
	v_add_f32_e32 v124, v124, v125
	v_add_f32_e32 v96, v96, v97
	v_add_f32_e32 v100, v100, v101
	v_add_f32_e32 v104, v104, v105
	v_add_f32_e32 v108, v108, v109
	v_add_f32_e32 v114, v114, v115
	v_add_f32_e32 v118, v118, v119
	v_add_f32_e32 v122, v122, v123
	v_add_f32_e32 v126, v126, v127
	v_add_f32_e32 v98, v98, v99
	v_add_f32_e32 v102, v102, v103
	v_add_f32_e32 v106, v106, v107
	v_add_f32_e32 v110, v110, v111
	v_add_f32_e32 v112, v112, v114
	v_add_f32_e32 v116, v116, v118
	v_add_f32_e32 v120, v120, v122
	v_add_f32_e32 v124, v124, v126
	v_add_f32_e32 v96, v96, v98
	v_add_f32_e32 v100, v100, v102
	v_add_f32_e32 v104, v104, v106
	v_add_f32_e32 v108, v108, v110
	v_mov_b32_e32 v113, v112
	v_mov_b32_e32 v117, v116
	v_mov_b32_e32 v121, v120
	v_mov_b32_e32 v125, v124
	v_mov_b32_e32 v97, v96
	v_mov_b32_e32 v101, v100
	v_mov_b32_e32 v105, v104
	v_mov_b32_e32 v109, v108
	v_permlane16_swap_b32_e32 v113, v112
	v_permlane16_swap_b32_e32 v117, v116
	v_permlane16_swap_b32_e32 v121, v120
	v_permlane16_swap_b32_e32 v125, v124
	v_permlane16_swap_b32_e32 v97, v96
	v_permlane16_swap_b32_e32 v101, v100
	v_permlane16_swap_b32_e32 v105, v104
	v_permlane16_swap_b32_e32 v109, v108
	v_add_f32_e32 v112, v112, v113
	v_add_f32_e32 v116, v116, v117
	v_add_f32_e32 v120, v120, v121
	v_add_f32_e32 v124, v124, v125
	v_add_f32_e32 v96, v96, v97
	v_add_f32_e32 v100, v100, v101
	v_add_f32_e32 v104, v104, v105
	v_add_f32_e32 v108, v108, v109
	v_mov_b32_e32 v113, v112
	v_mov_b32_e32 v117, v116
	v_mov_b32_e32 v121, v120
	v_mov_b32_e32 v125, v124
	v_mov_b32_e32 v97, v96
	v_mov_b32_e32 v101, v100
	v_mov_b32_e32 v105, v104
	v_mov_b32_e32 v109, v108
	v_permlane32_swap_b32_e32 v113, v112
	v_permlane32_swap_b32_e32 v117, v116
	v_permlane32_swap_b32_e32 v121, v120
	v_permlane32_swap_b32_e32 v125, v124
	v_permlane32_swap_b32_e32 v97, v96
	v_permlane32_swap_b32_e32 v101, v100
	v_permlane32_swap_b32_e32 v105, v104
	v_permlane32_swap_b32_e32 v109, v108
	v_add_f32_e32 v112, v112, v113
	v_add_f32_e32 v116, v116, v117
	v_add_f32_e32 v120, v120, v121
	v_add_f32_e32 v124, v124, v125
	v_add_f32_e32 v96, v96, v97
	v_add_f32_e32 v100, v100, v101
	v_add_f32_e32 v104, v104, v105
	v_add_f32_e32 v108, v108, v109
	v_fmamk_f32 v112, v112, 0x3a800000, v158
	v_fmamk_f32 v116, v116, 0x3a800000, v158
	v_fmamk_f32 v120, v120, 0x3a800000, v158
	v_fmamk_f32 v124, v124, 0x3a800000, v158
	v_fmamk_f32 v96, v96, 0x3a800000, v158
	v_fmamk_f32 v100, v100, 0x3a800000, v158
	v_fmamk_f32 v104, v104, 0x3a800000, v158
	v_fmamk_f32 v108, v108, 0x3a800000, v158
	v_rsq_f32_e32 v226, v112
	v_rsq_f32_e32 v228, v116
	v_rsq_f32_e32 v230, v120
	v_rsq_f32_e32 v232, v124
	v_rsq_f32_e32 v234, v96
	v_rsq_f32_e32 v236, v100
	v_rsq_f32_e32 v238, v104
	v_rsq_f32_e32 v240, v108
	s_andn2_b64 vcc, exec, s[0:1]
	s_mov_b64 s[0:1], -1
	s_cbranch_vccnz .LBB0_1010
	s_andn2_b64 vcc, exec, s[4:5]
	s_cbranch_vccnz .LBB0_1009
	s_barrier
	s_branch .LBB0_1009
